# RoPE ladder: cos/sin loads hoisted before the ds_bpermute in all 32 steps (default-value v_mov moved above the masked loads in the 8 remaining steps)
# baseline (speedup 1.0000x reference)
.LBB0_155:
	s_lshl_b32 s9, s9, 10
	v_add_u32_e32 v196, s9, v191
	ds_read_b32 v168, v196
	s_lshl_b32 s22, s8, 8
	s_lshl_b32 s35, s10, 8
	v_or_b32_e32 v164, s22, v182
	s_cmp_lt_i32 s8, 3
	s_waitcnt lgkmcnt(0)
	v_mov_b32_e32 v169, v168
	v_ashrrev_i32_e32 v165, 31, v164
	v_add_u32_e32 v166, s35, v155
	s_cselect_b64 s[70:71], -1, 0
	s_cmp_gt_i32 s8, 2
	s_mov_b64 s[8:9], -1
	v_pk_mul_f32 v[132:133], v[124:125], v[168:169]
	v_pk_mul_f32 v[128:129], v[120:121], v[168:169]
	s_cbranch_scc1 .LBB0_174
	s_cmp_lt_i32 s22, s89
	v_lshlrev_b32_e32 v120, 3, v166
	s_cselect_b64 s[8:9], -1, 0
	v_and_b32_e32 v152, 0xfe78, v120
	v_mov_b32_e32 v120, v168
	v_mov_b32_e32 v121, v168
	s_and_b64 s[8:9], s[30:31], s[8:9]
	v_pk_mul_f32 v[134:135], v[126:127], v[120:121]
	v_pk_mul_f32 v[130:131], v[122:123], v[120:121]
	s_and_b64 vcc, exec, s[8:9]
	s_cbranch_vccz .LBB0_164
	v_and_b32_e32 v125, 64, v195
	v_xor_b32_e32 v124, 16, v195
	v_add_u32_e32 v125, 64, v125
	v_cmp_lt_i32_e32 vcc, v124, v125
	v_mov_b64_e32 v[138:139], v[134:135]
	v_mov_b64_e32 v[142:143], v[130:131]
	v_cndmask_b32_e32 v124, v195, v124, vcc
	v_lshlrev_b32_e32 v124, 2, v124
	v_mov_b64_e32 v[136:137], v[132:133]
	v_mov_b64_e32 v[140:141], v[128:129]
	s_and_saveexec_b64 s[98:99], s[0:1]
	v_lshlrev_b32_e32 v240, 2, v152
	global_load_dwordx4 v[136:139], v240, s[64:65]
	global_load_dwordx4 v[140:143], v240, s[44:45]
	global_load_dwordx4 v[198:201], v240, s[64:65] offset:16
	global_load_dwordx4 v[202:205], v240, s[44:45] offset:16
	s_mov_b64 exec, s[98:99]
	ds_bpermute_b32 v172, v124, v132
	ds_bpermute_b32 v174, v124, v128
	ds_bpermute_b32 v173, v124, v133
	ds_bpermute_b32 v175, v124, v129
	ds_bpermute_b32 v170, v124, v134
	ds_bpermute_b32 v178, v124, v130
	ds_bpermute_b32 v171, v124, v135
	ds_bpermute_b32 v179, v124, v131
	s_and_saveexec_b64 s[8:9], s[0:1]
	s_cbranch_execz .LBB0_163
	s_waitcnt vmcnt(0)
	v_pk_mul_f32 v[124:125], v[134:135], v[138:139]
	v_pk_mul_f32 v[134:135], v[132:133], v[136:137]
	s_waitcnt lgkmcnt(5)
	v_pk_mul_f32 v[172:173], v[140:141], v[172:173]
	s_waitcnt lgkmcnt(1)
	v_pk_mul_f32 v[176:177], v[142:143], v[170:171]
	v_pk_mul_f32 v[130:131], v[130:131], v[200:201]
	v_pk_mul_f32 v[170:171], v[128:129], v[198:199]
	v_pk_mul_f32 v[174:175], v[202:203], v[174:175]
	s_waitcnt lgkmcnt(0)
	v_pk_mul_f32 v[178:179], v[204:205], v[178:179]
	s_and_saveexec_b64 s[10:11], s[4:5]
	s_xor_b64 s[10:11], exec, s[10:11]
	v_pk_add_f32 v[138:139], v[124:125], v[176:177]
	v_pk_add_f32 v[136:137], v[134:135], v[172:173]
	v_pk_add_f32 v[142:143], v[130:131], v[178:179]
	v_pk_add_f32 v[140:141], v[170:171], v[174:175]
	s_andn2_saveexec_b64 s[10:11], s[10:11]
	v_sub_f32_e32 v139, v125, v177
	v_sub_f32_e32 v138, v124, v176
	v_sub_f32_e32 v137, v135, v173
	v_sub_f32_e32 v136, v134, v172
	v_sub_f32_e32 v143, v131, v179
	v_sub_f32_e32 v142, v130, v178
	v_sub_f32_e32 v141, v171, v175
	v_sub_f32_e32 v140, v170, v174
	s_or_b64 exec, exec, s[10:11]

.LBB0_176:
	ds_read_b32 v130, v196 offset:64
	s_nop 0
	v_cndmask_b32_e64 v112, 0, 1, s[70:71]
	v_cndmask_b32_e64 v114, 0, 1, s[30:31]
	v_add_u32_e32 v128, s35, v184
	s_mov_b64 s[78:79], -1
	s_waitcnt lgkmcnt(0)
	v_mov_b32_e32 v131, v130
	v_cmp_ne_u32_e64 s[10:11], 1, v112
	s_andn2_b64 vcc, exec, s[70:71]
	v_pk_mul_f32 v[116:117], v[108:109], v[130:131]
	v_pk_mul_f32 v[112:113], v[104:105], v[130:131]
	v_cmp_ne_u32_e64 s[8:9], 1, v114
	s_cbranch_vccnz .LBB0_195
	v_lshlrev_b32_e32 v104, 3, v128
	v_and_b32_e32 v129, 0xfef8, v104
	v_mov_b32_e32 v104, v130
	v_mov_b32_e32 v105, v130
	v_pk_mul_f32 v[118:119], v[110:111], v[104:105]
	s_and_b64 vcc, exec, s[8:9]
	v_pk_mul_f32 v[114:115], v[106:107], v[104:105]
	s_cbranch_vccnz .LBB0_185
	v_and_b32_e32 v109, 64, v195
	v_xor_b32_e32 v108, 16, v195
	v_add_u32_e32 v109, 64, v109
	v_cmp_lt_i32_e32 vcc, v108, v109
	v_mov_b64_e32 v[122:123], v[118:119]
	v_mov_b64_e32 v[126:127], v[114:115]
	v_cndmask_b32_e32 v108, v195, v108, vcc
	v_lshlrev_b32_e32 v108, 2, v108
	v_mov_b64_e32 v[120:121], v[116:117]
	v_mov_b64_e32 v[124:125], v[112:113]
	s_and_saveexec_b64 s[98:99], s[0:1]
	v_lshlrev_b32_e32 v240, 2, v129
	global_load_dwordx4 v[120:123], v240, s[64:65]
	global_load_dwordx4 v[124:127], v240, s[44:45]
	global_load_dwordx4 v[166:169], v240, s[64:65] offset:16
	global_load_dwordx4 v[170:173], v240, s[44:45] offset:16
	s_mov_b64 exec, s[98:99]
	ds_bpermute_b32 v134, v108, v116
	ds_bpermute_b32 v136, v108, v112
	ds_bpermute_b32 v135, v108, v117
	ds_bpermute_b32 v137, v108, v113
	ds_bpermute_b32 v132, v108, v118
	ds_bpermute_b32 v140, v108, v114
	ds_bpermute_b32 v133, v108, v119
	ds_bpermute_b32 v141, v108, v115
	s_and_saveexec_b64 s[70:71], s[0:1]
	s_cbranch_execz .LBB0_184
	s_waitcnt vmcnt(0)
	v_pk_mul_f32 v[108:109], v[118:119], v[122:123]
	v_pk_mul_f32 v[118:119], v[116:117], v[120:121]
	s_waitcnt lgkmcnt(5)
	v_pk_mul_f32 v[134:135], v[124:125], v[134:135]
	s_waitcnt lgkmcnt(1)
	v_pk_mul_f32 v[138:139], v[126:127], v[132:133]
	v_pk_mul_f32 v[114:115], v[114:115], v[168:169]
	v_pk_mul_f32 v[132:133], v[112:113], v[166:167]
	v_pk_mul_f32 v[136:137], v[170:171], v[136:137]
	s_waitcnt lgkmcnt(0)
	v_pk_mul_f32 v[140:141], v[172:173], v[140:141]
	s_and_saveexec_b64 s[78:79], s[4:5]
	s_xor_b64 s[78:79], exec, s[78:79]
	v_pk_add_f32 v[122:123], v[108:109], v[138:139]
	v_pk_add_f32 v[120:121], v[118:119], v[134:135]
	v_pk_add_f32 v[126:127], v[114:115], v[140:141]
	v_pk_add_f32 v[124:125], v[132:133], v[136:137]
	s_andn2_saveexec_b64 s[78:79], s[78:79]
	v_sub_f32_e32 v123, v109, v139
	v_sub_f32_e32 v122, v108, v138
	v_sub_f32_e32 v121, v119, v135
	v_sub_f32_e32 v120, v118, v134
	v_sub_f32_e32 v127, v115, v141
	v_sub_f32_e32 v126, v114, v140
	v_sub_f32_e32 v125, v133, v137
	v_sub_f32_e32 v124, v132, v136
	s_or_b64 exec, exec, s[78:79]

.LBB0_197:
	ds_read_b32 v114, v196 offset:128
	v_add_u32_e32 v112, s35, v185
	s_mov_b64 s[70:71], -1
	s_and_b64 vcc, exec, s[10:11]
	s_waitcnt lgkmcnt(0)
	v_mov_b32_e32 v115, v114
	v_pk_mul_f32 v[100:101], v[92:93], v[114:115]
	v_pk_mul_f32 v[96:97], v[88:89], v[114:115]
	s_cbranch_vccnz .LBB0_216
	v_lshlrev_b32_e32 v88, 3, v112
	v_and_b32_e32 v113, 0xff78, v88
	v_mov_b32_e32 v88, v114
	v_mov_b32_e32 v89, v114
	v_pk_mul_f32 v[102:103], v[94:95], v[88:89]
	s_and_b64 vcc, exec, s[8:9]
	v_pk_mul_f32 v[98:99], v[90:91], v[88:89]
	s_cbranch_vccnz .LBB0_206
	v_and_b32_e32 v93, 64, v195
	v_xor_b32_e32 v92, 16, v195
	v_add_u32_e32 v93, 64, v93
	v_cmp_lt_i32_e32 vcc, v92, v93
	v_mov_b64_e32 v[106:107], v[102:103]
	v_mov_b64_e32 v[110:111], v[98:99]
	v_cndmask_b32_e32 v92, v195, v92, vcc
	v_lshlrev_b32_e32 v92, 2, v92
	v_mov_b64_e32 v[104:105], v[100:101]
	v_mov_b64_e32 v[108:109], v[96:97]
	s_and_saveexec_b64 s[98:99], s[0:1]
	v_lshlrev_b32_e32 v240, 2, v113
	global_load_dwordx4 v[104:107], v240, s[64:65]
	global_load_dwordx4 v[108:111], v240, s[44:45]
	global_load_dwordx4 v[126:129], v240, s[64:65] offset:16
	global_load_dwordx4 v[130:133], v240, s[44:45] offset:16
	s_mov_b64 exec, s[98:99]
	ds_bpermute_b32 v118, v92, v100
	ds_bpermute_b32 v120, v92, v96
	ds_bpermute_b32 v119, v92, v101
	ds_bpermute_b32 v121, v92, v97
	ds_bpermute_b32 v116, v92, v102
	ds_bpermute_b32 v124, v92, v98
	ds_bpermute_b32 v117, v92, v103
	ds_bpermute_b32 v125, v92, v99
	s_and_saveexec_b64 s[70:71], s[0:1]
	s_cbranch_execz .LBB0_205
	s_waitcnt vmcnt(0)
	v_pk_mul_f32 v[92:93], v[102:103], v[106:107]
	v_pk_mul_f32 v[102:103], v[100:101], v[104:105]
	s_waitcnt lgkmcnt(5)
	v_pk_mul_f32 v[118:119], v[108:109], v[118:119]
	s_waitcnt lgkmcnt(1)
	v_pk_mul_f32 v[122:123], v[110:111], v[116:117]
	v_pk_mul_f32 v[98:99], v[98:99], v[128:129]
	v_pk_mul_f32 v[116:117], v[96:97], v[126:127]
	v_pk_mul_f32 v[120:121], v[130:131], v[120:121]
	s_waitcnt lgkmcnt(0)
	v_pk_mul_f32 v[124:125], v[132:133], v[124:125]
	s_and_saveexec_b64 s[78:79], s[4:5]
	s_xor_b64 s[78:79], exec, s[78:79]
	v_pk_add_f32 v[106:107], v[92:93], v[122:123]
	v_pk_add_f32 v[104:105], v[102:103], v[118:119]
	v_pk_add_f32 v[110:111], v[98:99], v[124:125]
	v_pk_add_f32 v[108:109], v[116:117], v[120:121]
	s_andn2_saveexec_b64 s[78:79], s[78:79]
	v_sub_f32_e32 v107, v93, v123
	v_sub_f32_e32 v106, v92, v122
	v_sub_f32_e32 v105, v103, v119
	v_sub_f32_e32 v104, v102, v118
	v_sub_f32_e32 v111, v99, v125
	v_sub_f32_e32 v110, v98, v124
	v_sub_f32_e32 v109, v117, v121
	v_sub_f32_e32 v108, v116, v120
	s_or_b64 exec, exec, s[78:79]

.LBB0_218:
	ds_read_b32 v98, v196 offset:192
	v_add_u32_e32 v96, s35, v186
	s_mov_b64 s[70:71], -1
	s_and_b64 vcc, exec, s[10:11]
	s_waitcnt lgkmcnt(0)
	v_mov_b32_e32 v99, v98
	v_pk_mul_f32 v[84:85], v[76:77], v[98:99]
	v_pk_mul_f32 v[80:81], v[72:73], v[98:99]
	s_cbranch_vccnz .LBB0_237
	v_lshlrev_b32_e32 v72, 3, v96
	v_and_b32_e32 v97, 0xfff8, v72
	v_mov_b32_e32 v72, v98
	v_mov_b32_e32 v73, v98
	v_pk_mul_f32 v[86:87], v[78:79], v[72:73]
	s_and_b64 vcc, exec, s[8:9]
	v_pk_mul_f32 v[82:83], v[74:75], v[72:73]
	s_cbranch_vccnz .LBB0_227
	v_and_b32_e32 v77, 64, v195
	v_xor_b32_e32 v76, 16, v195
	v_add_u32_e32 v77, 64, v77
	v_cmp_lt_i32_e32 vcc, v76, v77
	v_mov_b64_e32 v[90:91], v[86:87]
	v_mov_b64_e32 v[94:95], v[82:83]
	v_cndmask_b32_e32 v76, v195, v76, vcc
	v_lshlrev_b32_e32 v76, 2, v76
	v_mov_b64_e32 v[88:89], v[84:85]
	v_mov_b64_e32 v[92:93], v[80:81]
	s_and_saveexec_b64 s[98:99], s[0:1]
	v_lshlrev_b32_e32 v240, 2, v97
	global_load_dwordx4 v[88:91], v240, s[64:65]
	global_load_dwordx4 v[92:95], v240, s[44:45]
	global_load_dwordx4 v[110:113], v240, s[64:65] offset:16
	global_load_dwordx4 v[114:117], v240, s[44:45] offset:16
	s_mov_b64 exec, s[98:99]
	ds_bpermute_b32 v102, v76, v84
	ds_bpermute_b32 v104, v76, v80
	ds_bpermute_b32 v103, v76, v85
	ds_bpermute_b32 v105, v76, v81
	ds_bpermute_b32 v100, v76, v86
	ds_bpermute_b32 v108, v76, v82
	ds_bpermute_b32 v101, v76, v87
	ds_bpermute_b32 v109, v76, v83
	s_and_saveexec_b64 s[70:71], s[0:1]
	s_cbranch_execz .LBB0_226
	s_waitcnt vmcnt(0)
	v_pk_mul_f32 v[76:77], v[86:87], v[90:91]
	v_pk_mul_f32 v[86:87], v[84:85], v[88:89]
	s_waitcnt lgkmcnt(5)
	v_pk_mul_f32 v[102:103], v[92:93], v[102:103]
	s_waitcnt lgkmcnt(1)
	v_pk_mul_f32 v[106:107], v[94:95], v[100:101]
	v_pk_mul_f32 v[82:83], v[82:83], v[112:113]
	v_pk_mul_f32 v[100:101], v[80:81], v[110:111]
	v_pk_mul_f32 v[104:105], v[114:115], v[104:105]
	s_waitcnt lgkmcnt(0)
	v_pk_mul_f32 v[108:109], v[116:117], v[108:109]
	s_and_saveexec_b64 s[78:79], s[4:5]
	s_xor_b64 s[78:79], exec, s[78:79]
	v_pk_add_f32 v[90:91], v[76:77], v[106:107]
	v_pk_add_f32 v[88:89], v[86:87], v[102:103]
	v_pk_add_f32 v[94:95], v[82:83], v[108:109]
	v_pk_add_f32 v[92:93], v[100:101], v[104:105]
	s_andn2_saveexec_b64 s[78:79], s[78:79]
	v_sub_f32_e32 v91, v77, v107
	v_sub_f32_e32 v90, v76, v106
	v_sub_f32_e32 v89, v87, v103
	v_sub_f32_e32 v88, v86, v102
	v_sub_f32_e32 v95, v83, v109
	v_sub_f32_e32 v94, v82, v108
	v_sub_f32_e32 v93, v101, v105
	v_sub_f32_e32 v92, v100, v104
	s_or_b64 exec, exec, s[78:79]

.LBB0_239:
	ds_read_b32 v82, v196 offset:512
	v_add_u32_e32 v80, s35, v187
	s_mov_b64 s[70:71], -1
	s_and_b64 vcc, exec, s[10:11]
	s_waitcnt lgkmcnt(0)
	v_mov_b32_e32 v83, v82
	v_pk_mul_f32 v[68:69], v[60:61], v[82:83]
	v_pk_mul_f32 v[64:65], v[56:57], v[82:83]
	s_cbranch_vccnz .LBB0_258
	v_lshlrev_b32_e32 v56, 3, v80
	v_and_b32_e32 v81, 0xfe78, v56
	v_mov_b32_e32 v56, v82
	v_mov_b32_e32 v57, v82
	v_pk_mul_f32 v[70:71], v[62:63], v[56:57]
	s_and_b64 vcc, exec, s[8:9]
	v_pk_mul_f32 v[66:67], v[58:59], v[56:57]
	s_cbranch_vccnz .LBB0_248
	v_and_b32_e32 v61, 64, v195
	v_xor_b32_e32 v60, 16, v195
	v_add_u32_e32 v61, 64, v61
	v_cmp_lt_i32_e32 vcc, v60, v61
	v_mov_b64_e32 v[74:75], v[70:71]
	v_mov_b64_e32 v[78:79], v[66:67]
	v_cndmask_b32_e32 v60, v195, v60, vcc
	v_lshlrev_b32_e32 v60, 2, v60
	v_mov_b64_e32 v[72:73], v[68:69]
	v_mov_b64_e32 v[76:77], v[64:65]
	s_and_saveexec_b64 s[98:99], s[0:1]
	v_lshlrev_b32_e32 v240, 2, v81
	global_load_dwordx4 v[72:75], v240, s[64:65]
	global_load_dwordx4 v[76:79], v240, s[44:45]
	global_load_dwordx4 v[94:97], v240, s[64:65] offset:16
	global_load_dwordx4 v[98:101], v240, s[44:45] offset:16
	s_mov_b64 exec, s[98:99]
	ds_bpermute_b32 v86, v60, v68
	ds_bpermute_b32 v88, v60, v64
	ds_bpermute_b32 v87, v60, v69
	ds_bpermute_b32 v89, v60, v65
	ds_bpermute_b32 v84, v60, v70
	ds_bpermute_b32 v92, v60, v66
	ds_bpermute_b32 v85, v60, v71
	ds_bpermute_b32 v93, v60, v67
	s_and_saveexec_b64 s[70:71], s[0:1]
	s_cbranch_execz .LBB0_247
	s_waitcnt vmcnt(0)
	v_pk_mul_f32 v[60:61], v[70:71], v[74:75]
	v_pk_mul_f32 v[70:71], v[68:69], v[72:73]
	s_waitcnt lgkmcnt(5)
	v_pk_mul_f32 v[86:87], v[76:77], v[86:87]
	s_waitcnt lgkmcnt(1)
	v_pk_mul_f32 v[90:91], v[78:79], v[84:85]
	v_pk_mul_f32 v[66:67], v[66:67], v[96:97]
	v_pk_mul_f32 v[84:85], v[64:65], v[94:95]
	v_pk_mul_f32 v[88:89], v[98:99], v[88:89]
	s_waitcnt lgkmcnt(0)
	v_pk_mul_f32 v[92:93], v[100:101], v[92:93]
	s_and_saveexec_b64 s[78:79], s[4:5]
	s_xor_b64 s[78:79], exec, s[78:79]
	v_pk_add_f32 v[74:75], v[60:61], v[90:91]
	v_pk_add_f32 v[72:73], v[70:71], v[86:87]
	v_pk_add_f32 v[78:79], v[66:67], v[92:93]
	v_pk_add_f32 v[76:77], v[84:85], v[88:89]
	s_andn2_saveexec_b64 s[78:79], s[78:79]
	v_sub_f32_e32 v75, v61, v91
	v_sub_f32_e32 v74, v60, v90
	v_sub_f32_e32 v73, v71, v87
	v_sub_f32_e32 v72, v70, v86
	v_sub_f32_e32 v79, v67, v93
	v_sub_f32_e32 v78, v66, v92
	v_sub_f32_e32 v77, v85, v89
	v_sub_f32_e32 v76, v84, v88
	s_or_b64 exec, exec, s[78:79]

.LBB0_260:
	ds_read_b32 v66, v196 offset:576
	v_add_u32_e32 v64, s35, v188
	s_mov_b64 s[70:71], -1
	s_and_b64 vcc, exec, s[10:11]
	s_waitcnt lgkmcnt(0)
	v_mov_b32_e32 v67, v66
	v_pk_mul_f32 v[52:53], v[44:45], v[66:67]
	v_pk_mul_f32 v[48:49], v[40:41], v[66:67]
	s_cbranch_vccnz .LBB0_279
	v_lshlrev_b32_e32 v40, 3, v64
	v_and_b32_e32 v65, 0xfef8, v40
	v_mov_b32_e32 v40, v66
	v_mov_b32_e32 v41, v66
	v_pk_mul_f32 v[54:55], v[46:47], v[40:41]
	s_and_b64 vcc, exec, s[8:9]
	v_pk_mul_f32 v[50:51], v[42:43], v[40:41]
	s_cbranch_vccnz .LBB0_269
	v_and_b32_e32 v45, 64, v195
	v_xor_b32_e32 v44, 16, v195
	v_add_u32_e32 v45, 64, v45
	v_cmp_lt_i32_e32 vcc, v44, v45
	v_mov_b64_e32 v[58:59], v[54:55]
	v_mov_b64_e32 v[62:63], v[50:51]
	v_cndmask_b32_e32 v44, v195, v44, vcc
	v_lshlrev_b32_e32 v44, 2, v44
	v_mov_b64_e32 v[56:57], v[52:53]
	v_mov_b64_e32 v[60:61], v[48:49]
	s_and_saveexec_b64 s[98:99], s[0:1]
	v_lshlrev_b32_e32 v240, 2, v65
	global_load_dwordx4 v[56:59], v240, s[64:65]
	global_load_dwordx4 v[60:63], v240, s[44:45]
	global_load_dwordx4 v[78:81], v240, s[64:65] offset:16
	global_load_dwordx4 v[82:85], v240, s[44:45] offset:16
	s_mov_b64 exec, s[98:99]
	ds_bpermute_b32 v70, v44, v52
	ds_bpermute_b32 v72, v44, v48
	ds_bpermute_b32 v71, v44, v53
	ds_bpermute_b32 v73, v44, v49
	ds_bpermute_b32 v68, v44, v54
	ds_bpermute_b32 v76, v44, v50
	ds_bpermute_b32 v69, v44, v55
	ds_bpermute_b32 v77, v44, v51
	s_and_saveexec_b64 s[70:71], s[0:1]
	s_cbranch_execz .LBB0_268
	s_waitcnt vmcnt(0)
	v_pk_mul_f32 v[44:45], v[54:55], v[58:59]
	v_pk_mul_f32 v[54:55], v[52:53], v[56:57]
	s_waitcnt lgkmcnt(5)
	v_pk_mul_f32 v[70:71], v[60:61], v[70:71]
	s_waitcnt lgkmcnt(1)
	v_pk_mul_f32 v[74:75], v[62:63], v[68:69]
	v_pk_mul_f32 v[50:51], v[50:51], v[80:81]
	v_pk_mul_f32 v[68:69], v[48:49], v[78:79]
	v_pk_mul_f32 v[72:73], v[82:83], v[72:73]
	s_waitcnt lgkmcnt(0)
	v_pk_mul_f32 v[76:77], v[84:85], v[76:77]
	s_and_saveexec_b64 s[78:79], s[4:5]
	s_xor_b64 s[78:79], exec, s[78:79]
	v_pk_add_f32 v[58:59], v[44:45], v[74:75]
	v_pk_add_f32 v[56:57], v[54:55], v[70:71]
	v_pk_add_f32 v[62:63], v[50:51], v[76:77]
	v_pk_add_f32 v[60:61], v[68:69], v[72:73]
	s_andn2_saveexec_b64 s[78:79], s[78:79]
	v_sub_f32_e32 v59, v45, v75
	v_sub_f32_e32 v58, v44, v74
	v_sub_f32_e32 v57, v55, v71
	v_sub_f32_e32 v56, v54, v70
	v_sub_f32_e32 v63, v51, v77
	v_sub_f32_e32 v62, v50, v76
	v_sub_f32_e32 v61, v69, v73
	v_sub_f32_e32 v60, v68, v72
	s_or_b64 exec, exec, s[78:79]

.LBB0_281:
	ds_read_b32 v50, v196 offset:640
	v_add_u32_e32 v48, s35, v189
	s_mov_b64 s[70:71], -1
	s_and_b64 vcc, exec, s[10:11]
	s_waitcnt lgkmcnt(0)
	v_mov_b32_e32 v51, v50
	v_pk_mul_f32 v[36:37], v[28:29], v[50:51]
	v_pk_mul_f32 v[32:33], v[24:25], v[50:51]
	s_cbranch_vccnz .LBB0_300
	v_lshlrev_b32_e32 v24, 3, v48
	v_and_b32_e32 v49, 0xff78, v24
	v_mov_b32_e32 v24, v50
	v_mov_b32_e32 v25, v50
	v_pk_mul_f32 v[38:39], v[30:31], v[24:25]
	s_and_b64 vcc, exec, s[8:9]
	v_pk_mul_f32 v[34:35], v[26:27], v[24:25]
	s_cbranch_vccnz .LBB0_290
	v_and_b32_e32 v29, 64, v195
	v_xor_b32_e32 v28, 16, v195
	v_add_u32_e32 v29, 64, v29
	v_cmp_lt_i32_e32 vcc, v28, v29
	v_mov_b64_e32 v[42:43], v[38:39]
	v_mov_b64_e32 v[46:47], v[34:35]
	v_cndmask_b32_e32 v28, v195, v28, vcc
	v_lshlrev_b32_e32 v28, 2, v28
	v_mov_b64_e32 v[40:41], v[36:37]
	v_mov_b64_e32 v[44:45], v[32:33]
	s_and_saveexec_b64 s[98:99], s[0:1]
	v_lshlrev_b32_e32 v240, 2, v49
	global_load_dwordx4 v[40:43], v240, s[64:65]
	global_load_dwordx4 v[44:47], v240, s[44:45]
	global_load_dwordx4 v[62:65], v240, s[64:65] offset:16
	global_load_dwordx4 v[66:69], v240, s[44:45] offset:16
	s_mov_b64 exec, s[98:99]
	ds_bpermute_b32 v54, v28, v36
	ds_bpermute_b32 v56, v28, v32
	ds_bpermute_b32 v55, v28, v37
	ds_bpermute_b32 v57, v28, v33
	ds_bpermute_b32 v52, v28, v38
	ds_bpermute_b32 v60, v28, v34
	ds_bpermute_b32 v53, v28, v39
	ds_bpermute_b32 v61, v28, v35
	s_and_saveexec_b64 s[70:71], s[0:1]
	s_cbranch_execz .LBB0_289
	s_waitcnt vmcnt(0)
	v_pk_mul_f32 v[28:29], v[38:39], v[42:43]
	v_pk_mul_f32 v[38:39], v[36:37], v[40:41]
	s_waitcnt lgkmcnt(5)
	v_pk_mul_f32 v[54:55], v[44:45], v[54:55]
	s_waitcnt lgkmcnt(1)
	v_pk_mul_f32 v[58:59], v[46:47], v[52:53]
	v_pk_mul_f32 v[34:35], v[34:35], v[64:65]
	v_pk_mul_f32 v[52:53], v[32:33], v[62:63]
	v_pk_mul_f32 v[56:57], v[66:67], v[56:57]
	s_waitcnt lgkmcnt(0)
	v_pk_mul_f32 v[60:61], v[68:69], v[60:61]
	s_and_saveexec_b64 s[78:79], s[4:5]
	s_xor_b64 s[78:79], exec, s[78:79]
	v_pk_add_f32 v[42:43], v[28:29], v[58:59]
	v_pk_add_f32 v[40:41], v[38:39], v[54:55]
	v_pk_add_f32 v[46:47], v[34:35], v[60:61]
	v_pk_add_f32 v[44:45], v[52:53], v[56:57]
	s_andn2_saveexec_b64 s[78:79], s[78:79]
	v_sub_f32_e32 v43, v29, v59
	v_sub_f32_e32 v42, v28, v58
	v_sub_f32_e32 v41, v39, v55
	v_sub_f32_e32 v40, v38, v54
	v_sub_f32_e32 v47, v35, v61
	v_sub_f32_e32 v46, v34, v60
	v_sub_f32_e32 v45, v53, v57
	v_sub_f32_e32 v44, v52, v56
	s_or_b64 exec, exec, s[78:79]

.LBB0_305:
	v_lshlrev_b32_e32 v8, 3, v32
	v_and_b32_e32 v33, 0xfff8, v8
	v_mov_b32_e32 v8, v34
	v_mov_b32_e32 v9, v34
	v_pk_mul_f32 v[22:23], v[14:15], v[8:9]
	s_and_b64 vcc, exec, s[8:9]
	v_pk_mul_f32 v[18:19], v[10:11], v[8:9]
	s_cbranch_vccnz .LBB0_313
	v_and_b32_e32 v13, 64, v195
	v_xor_b32_e32 v12, 16, v195
	v_add_u32_e32 v13, 64, v13
	v_cmp_lt_i32_e32 vcc, v12, v13
	v_mov_b64_e32 v[26:27], v[22:23]
	v_mov_b64_e32 v[30:31], v[18:19]
	v_cndmask_b32_e32 v12, v195, v12, vcc
	v_lshlrev_b32_e32 v12, 2, v12
	v_mov_b64_e32 v[24:25], v[20:21]
	v_mov_b64_e32 v[28:29], v[16:17]
	s_and_saveexec_b64 s[98:99], s[0:1]
	v_lshlrev_b32_e32 v240, 2, v33
	global_load_dwordx4 v[24:27], v240, s[64:65]
	global_load_dwordx4 v[28:31], v240, s[44:45]
	global_load_dwordx4 v[46:49], v240, s[64:65] offset:16
	global_load_dwordx4 v[50:53], v240, s[44:45] offset:16
	s_mov_b64 exec, s[98:99]
	ds_bpermute_b32 v38, v12, v20
	ds_bpermute_b32 v40, v12, v16
	ds_bpermute_b32 v39, v12, v21
	ds_bpermute_b32 v41, v12, v17
	ds_bpermute_b32 v36, v12, v22
	ds_bpermute_b32 v44, v12, v18
	ds_bpermute_b32 v37, v12, v23
	ds_bpermute_b32 v45, v12, v19
	s_and_saveexec_b64 s[8:9], s[0:1]
	s_cbranch_execz .LBB0_312
	s_waitcnt vmcnt(0)
	v_pk_mul_f32 v[12:13], v[22:23], v[26:27]
	v_pk_mul_f32 v[22:23], v[20:21], v[24:25]
	s_waitcnt lgkmcnt(5)
	v_pk_mul_f32 v[38:39], v[28:29], v[38:39]
	s_waitcnt lgkmcnt(1)
	v_pk_mul_f32 v[42:43], v[30:31], v[36:37]
	v_pk_mul_f32 v[18:19], v[18:19], v[48:49]
	v_pk_mul_f32 v[36:37], v[16:17], v[46:47]
	v_pk_mul_f32 v[40:41], v[50:51], v[40:41]
	s_waitcnt lgkmcnt(0)
	v_pk_mul_f32 v[44:45], v[52:53], v[44:45]
	s_and_saveexec_b64 s[10:11], s[4:5]
	s_xor_b64 s[10:11], exec, s[10:11]
	v_pk_add_f32 v[26:27], v[12:13], v[42:43]
	v_pk_add_f32 v[24:25], v[22:23], v[38:39]
	v_pk_add_f32 v[30:31], v[18:19], v[44:45]
	v_pk_add_f32 v[28:29], v[36:37], v[40:41]
	s_andn2_saveexec_b64 s[10:11], s[10:11]
	v_sub_f32_e32 v27, v13, v43
	v_sub_f32_e32 v26, v12, v42
	v_sub_f32_e32 v25, v23, v39
	v_sub_f32_e32 v24, v22, v38
	v_sub_f32_e32 v31, v19, v45
	v_sub_f32_e32 v30, v18, v44
	v_sub_f32_e32 v29, v37, v41
	v_sub_f32_e32 v28, v36, v40
	s_or_b64 exec, exec, s[10:11]
